# phase0 fold_item (W_in Fourier fold) moved from scalar v_fmac loop to v_mfma_f32_16x16x4_f32, same k-ordered fma chain (bit-identical)
# speedup vs baseline: 1.0062x; 1.0062x over previous
.LBB0_22:
	s_barrier
	s_and_saveexec_b64 s[24:25], s[4:5]
	ds_write2st64_b32 v5, v1, v16 offset0:129 offset1:131
	s_or_b64 exec, exec, s[24:25]
	s_ashr_i32 s24, s48, 7
	s_lshl_b32 s25, s48, 4
	s_and_b32 s26, s25, 0x7c0
	s_and_b32 s30, s48, 3
	s_lshl_b32 s27, s24, 11
	s_or_b32 s27, s27, s26
	s_lshl_b32 s28, s30, 9
	s_addk_i32 s28, 0x4000
	s_movk_i32 s29, 0x1fc
	v_readlane_b32 s34, v253, 8
	v_readlane_b32 s35, v253, 9
	s_mul_i32 s36, s24, 0x3400
	s_lshl_b32 s37, s30, 7
	s_add_i32 s36, s36, s37
	s_addk_i32 s36, 0x1000
	v_lshrrev_b32_e32 v10, 6, v82
	v_and_b32_e32 v10, 3, v10
	v_and_b32_e32 v11, 15, v84
	v_lshrrev_b32_e32 v12, 4, v84
	v_lshrrev_b32_e32 v13, 8, v82
	v_lshl_add_u32 v14, v10, 4, v11
	v_add_u32_e32 v14, s27, v14
	v_mul_u32_u24_e32 v14, s44, v14
	v_lshl_add_u32 v15, v12, 2, s28
	v_add_u32_e32 v14, v14, v15
	global_load_dword v182, v14, s[66:67]
	global_load_dword v183, v14, s[66:67] offset:16
	global_load_dword v184, v14, s[66:67] offset:32
	global_load_dword v185, v14, s[66:67] offset:48
	global_load_dword v186, v14, s[66:67] offset:64
	global_load_dword v187, v14, s[66:67] offset:80
	global_load_dword v188, v14, s[66:67] offset:96
	global_load_dword v189, v14, s[66:67] offset:112
	global_load_dword v190, v14, s[66:67] offset:128
	global_load_dword v191, v14, s[66:67] offset:144
	global_load_dword v192, v14, s[66:67] offset:160
	global_load_dword v193, v14, s[66:67] offset:176
	global_load_dword v194, v14, s[66:67] offset:192
	global_load_dword v195, v14, s[66:67] offset:208
	global_load_dword v196, v14, s[66:67] offset:224
	global_load_dword v197, v14, s[66:67] offset:240
	global_load_dword v198, v14, s[66:67] offset:256
	global_load_dword v199, v14, s[66:67] offset:272
	global_load_dword v200, v14, s[66:67] offset:288
	global_load_dword v201, v14, s[66:67] offset:304
	global_load_dword v202, v14, s[66:67] offset:320
	global_load_dword v203, v14, s[66:67] offset:336
	global_load_dword v204, v14, s[66:67] offset:352
	global_load_dword v205, v14, s[66:67] offset:368
	global_load_dword v206, v14, s[66:67] offset:384
	global_load_dword v207, v14, s[66:67] offset:400
	global_load_dword v208, v14, s[66:67] offset:416
	global_load_dword v209, v14, s[66:67] offset:432
	global_load_dword v210, v14, s[66:67] offset:448
	global_load_dword v211, v14, s[66:67] offset:464
	global_load_dword v212, v14, s[66:67] offset:480
	global_load_dword v213, v14, s[66:67] offset:496
	v_lshl_add_u32 v40, v13, 6, v11
	v_add_u32_e32 v40, s36, v40
	v_lshlrev_b32_e32 v40, 12, v40
	v_lshl_add_u32 v41, v10, 4, s26
	v_lshl_add_u32 v41, v12, 2, v41
	v_lshl_add_u32 v40, v41, 1, v40
	v_lshlrev_b32_e32 v42, 5, v13
	v_lshrrev_b32_e32 v43, 1, v11
	v_add_u32_e32 v42, v42, v43
	v_and_b32_e32 v43, 1, v11
	v_lshlrev_b32_e32 v43, 9, v43
	v_lshl_or_b32 v44, v13, 4, v11
	v_cmp_eq_u32_e32 vcc, 1, v44
	v_mov_b32_e32 v24, 0
	v_mov_b32_e32 v25, 0
	v_mov_b32_e32 v26, 0
	v_mov_b32_e32 v27, 0
	v_mov_b32_e32 v28, 0
	v_mov_b32_e32 v29, 0
	v_mov_b32_e32 v30, 0
	v_mov_b32_e32 v31, 0
	v_mov_b32_e32 v32, 0
	v_mov_b32_e32 v33, 0
	v_mov_b32_e32 v34, 0
	v_mov_b32_e32 v35, 0
	v_mov_b32_e32 v36, 0
	v_mov_b32_e32 v37, 0
	v_mov_b32_e32 v38, 0
	v_mov_b32_e32 v39, 0
	s_waitcnt lgkmcnt(0)
	s_barrier
	v_mov_b32_e32 v49, 64
	v_cndmask_b32_e32 v44, v42, v49, vcc
	v_cndmask_b32_e64 v48, v43, 0, vcc
	v_lshlrev_b32_e32 v45, 4, v44
	v_mul_u32_u24_e32 v46, v44, v12
	v_lshlrev_b32_e32 v46, 2, v46
	v_and_or_b32 v47, v46, s29, v48
	ds_read_b32 v214, v47 offset:33024
	v_add_u32_e32 v46, v46, v45
	v_and_or_b32 v47, v46, s29, v48
	ds_read_b32 v215, v47 offset:33024
	v_add_u32_e32 v46, v46, v45
	v_and_or_b32 v47, v46, s29, v48
	ds_read_b32 v216, v47 offset:33024
	v_add_u32_e32 v46, v46, v45
	v_and_or_b32 v47, v46, s29, v48
	ds_read_b32 v217, v47 offset:33024
	v_add_u32_e32 v46, v46, v45
	v_and_or_b32 v47, v46, s29, v48
	ds_read_b32 v218, v47 offset:33024
	v_add_u32_e32 v46, v46, v45
	v_and_or_b32 v47, v46, s29, v48
	ds_read_b32 v219, v47 offset:33024
	v_add_u32_e32 v46, v46, v45
	v_and_or_b32 v47, v46, s29, v48
	ds_read_b32 v221, v47 offset:33024
	v_add_u32_e32 v46, v46, v45
	v_and_or_b32 v47, v46, s29, v48
	ds_read_b32 v222, v47 offset:33024
	v_add_u32_e32 v46, v46, v45
	v_and_or_b32 v47, v46, s29, v48
	ds_read_b32 v223, v47 offset:33024
	v_add_u32_e32 v46, v46, v45
	v_and_or_b32 v47, v46, s29, v48
	ds_read_b32 v224, v47 offset:33024
	v_add_u32_e32 v46, v46, v45
	v_and_or_b32 v47, v46, s29, v48
	ds_read_b32 v225, v47 offset:33024
	v_add_u32_e32 v46, v46, v45
	v_and_or_b32 v47, v46, s29, v48
	ds_read_b32 v226, v47 offset:33024
	v_add_u32_e32 v46, v46, v45
	v_and_or_b32 v47, v46, s29, v48
	ds_read_b32 v227, v47 offset:33024
	v_add_u32_e32 v46, v46, v45
	v_and_or_b32 v47, v46, s29, v48
	ds_read_b32 v228, v47 offset:33024
	v_add_u32_e32 v46, v46, v45
	v_and_or_b32 v47, v46, s29, v48
	ds_read_b32 v229, v47 offset:33024
	v_add_u32_e32 v46, v46, v45
	v_and_or_b32 v47, v46, s29, v48
	ds_read_b32 v230, v47 offset:33024
	v_add_u32_e32 v46, v46, v45
	v_and_or_b32 v47, v46, s29, v48
	ds_read_b32 v231, v47 offset:33024
	v_add_u32_e32 v46, v46, v45
	v_and_or_b32 v47, v46, s29, v48
	ds_read_b32 v232, v47 offset:33024
	v_add_u32_e32 v46, v46, v45
	v_and_or_b32 v47, v46, s29, v48
	ds_read_b32 v233, v47 offset:33024
	v_add_u32_e32 v46, v46, v45
	v_and_or_b32 v47, v46, s29, v48
	ds_read_b32 v234, v47 offset:33024
	v_add_u32_e32 v46, v46, v45
	v_and_or_b32 v47, v46, s29, v48
	ds_read_b32 v235, v47 offset:33024
	v_add_u32_e32 v46, v46, v45
	v_and_or_b32 v47, v46, s29, v48
	ds_read_b32 v236, v47 offset:33024
	v_add_u32_e32 v46, v46, v45
	v_and_or_b32 v47, v46, s29, v48
	ds_read_b32 v237, v47 offset:33024
	v_add_u32_e32 v46, v46, v45
	v_and_or_b32 v47, v46, s29, v48
	ds_read_b32 v238, v47 offset:33024
	v_add_u32_e32 v46, v46, v45
	v_and_or_b32 v47, v46, s29, v48
	ds_read_b32 v239, v47 offset:33024
	v_add_u32_e32 v46, v46, v45
	v_and_or_b32 v47, v46, s29, v48
	ds_read_b32 v240, v47 offset:33024
	v_add_u32_e32 v46, v46, v45
	v_and_or_b32 v47, v46, s29, v48
	ds_read_b32 v241, v47 offset:33024
	v_add_u32_e32 v46, v46, v45
	v_and_or_b32 v47, v46, s29, v48
	ds_read_b32 v242, v47 offset:33024
	v_add_u32_e32 v46, v46, v45
	v_and_or_b32 v47, v46, s29, v48
	ds_read_b32 v243, v47 offset:33024
	v_add_u32_e32 v46, v46, v45
	v_and_or_b32 v47, v46, s29, v48
	ds_read_b32 v244, v47 offset:33024
	v_add_u32_e32 v46, v46, v45
	v_and_or_b32 v47, v46, s29, v48
	ds_read_b32 v245, v47 offset:33024
	v_add_u32_e32 v46, v46, v45
	v_and_or_b32 v47, v46, s29, v48
	ds_read_b32 v246, v47 offset:33024
	v_add_u32_e32 v46, v46, v45
	v_add_u32_e32 v44, 8, v42
	v_mov_b32_e32 v48, v43
	v_lshlrev_b32_e32 v45, 4, v44
	v_mul_u32_u24_e32 v46, v44, v12
	v_lshlrev_b32_e32 v46, 2, v46
	s_waitcnt vmcnt(31) lgkmcnt(15)
	v_mfma_f32_16x16x4_f32 v[24:27], v182, v214, v[24:27]
	v_and_or_b32 v47, v46, s29, v48
	ds_read_b32 v214, v47 offset:33024
	v_add_u32_e32 v46, v46, v45
	s_waitcnt vmcnt(30) lgkmcnt(15)
	v_mfma_f32_16x16x4_f32 v[24:27], v183, v215, v[24:27]
	v_and_or_b32 v47, v46, s29, v48
	ds_read_b32 v215, v47 offset:33024
	v_add_u32_e32 v46, v46, v45
	s_waitcnt vmcnt(29) lgkmcnt(15)
	v_mfma_f32_16x16x4_f32 v[24:27], v184, v216, v[24:27]
	v_and_or_b32 v47, v46, s29, v48
	ds_read_b32 v216, v47 offset:33024
	v_add_u32_e32 v46, v46, v45
	s_waitcnt vmcnt(28) lgkmcnt(15)
	v_mfma_f32_16x16x4_f32 v[24:27], v185, v217, v[24:27]
	v_and_or_b32 v47, v46, s29, v48
	ds_read_b32 v217, v47 offset:33024
	v_add_u32_e32 v46, v46, v45
	s_waitcnt vmcnt(27) lgkmcnt(15)
	v_mfma_f32_16x16x4_f32 v[24:27], v186, v218, v[24:27]
	v_and_or_b32 v47, v46, s29, v48
	ds_read_b32 v218, v47 offset:33024
	v_add_u32_e32 v46, v46, v45
	s_waitcnt vmcnt(26) lgkmcnt(15)
	v_mfma_f32_16x16x4_f32 v[24:27], v187, v219, v[24:27]
	v_and_or_b32 v47, v46, s29, v48
	ds_read_b32 v219, v47 offset:33024
	v_add_u32_e32 v46, v46, v45
	s_waitcnt vmcnt(25) lgkmcnt(15)
	v_mfma_f32_16x16x4_f32 v[24:27], v188, v221, v[24:27]
	v_and_or_b32 v47, v46, s29, v48
	ds_read_b32 v221, v47 offset:33024
	v_add_u32_e32 v46, v46, v45
	s_waitcnt vmcnt(24) lgkmcnt(15)
	v_mfma_f32_16x16x4_f32 v[24:27], v189, v222, v[24:27]
	v_and_or_b32 v47, v46, s29, v48
	ds_read_b32 v222, v47 offset:33024
	v_add_u32_e32 v46, v46, v45
	s_waitcnt vmcnt(23) lgkmcnt(15)
	v_mfma_f32_16x16x4_f32 v[24:27], v190, v223, v[24:27]
	v_and_or_b32 v47, v46, s29, v48
	ds_read_b32 v223, v47 offset:33024
	v_add_u32_e32 v46, v46, v45
	s_waitcnt vmcnt(22) lgkmcnt(15)
	v_mfma_f32_16x16x4_f32 v[24:27], v191, v224, v[24:27]
	v_and_or_b32 v47, v46, s29, v48
	ds_read_b32 v224, v47 offset:33024
	v_add_u32_e32 v46, v46, v45
	s_waitcnt vmcnt(21) lgkmcnt(15)
	v_mfma_f32_16x16x4_f32 v[24:27], v192, v225, v[24:27]
	v_and_or_b32 v47, v46, s29, v48
	ds_read_b32 v225, v47 offset:33024
	v_add_u32_e32 v46, v46, v45
	s_waitcnt vmcnt(20) lgkmcnt(15)
	v_mfma_f32_16x16x4_f32 v[24:27], v193, v226, v[24:27]
	v_and_or_b32 v47, v46, s29, v48
	ds_read_b32 v226, v47 offset:33024
	v_add_u32_e32 v46, v46, v45
	s_waitcnt vmcnt(19) lgkmcnt(15)
	v_mfma_f32_16x16x4_f32 v[24:27], v194, v227, v[24:27]
	v_and_or_b32 v47, v46, s29, v48
	ds_read_b32 v227, v47 offset:33024
	v_add_u32_e32 v46, v46, v45
	s_waitcnt vmcnt(18) lgkmcnt(15)
	v_mfma_f32_16x16x4_f32 v[24:27], v195, v228, v[24:27]
	v_and_or_b32 v47, v46, s29, v48
	ds_read_b32 v228, v47 offset:33024
	v_add_u32_e32 v46, v46, v45
	s_waitcnt vmcnt(17) lgkmcnt(15)
	v_mfma_f32_16x16x4_f32 v[24:27], v196, v229, v[24:27]
	v_and_or_b32 v47, v46, s29, v48
	ds_read_b32 v229, v47 offset:33024
	v_add_u32_e32 v46, v46, v45
	s_waitcnt vmcnt(16) lgkmcnt(15)
	v_mfma_f32_16x16x4_f32 v[24:27], v197, v230, v[24:27]
	v_and_or_b32 v47, v46, s29, v48
	ds_read_b32 v230, v47 offset:33024
	v_add_u32_e32 v46, v46, v45
	s_waitcnt vmcnt(15) lgkmcnt(15)
	v_mfma_f32_16x16x4_f32 v[24:27], v198, v231, v[24:27]
	v_and_or_b32 v47, v46, s29, v48
	ds_read_b32 v231, v47 offset:33024
	v_add_u32_e32 v46, v46, v45
	s_waitcnt vmcnt(14) lgkmcnt(15)
	v_mfma_f32_16x16x4_f32 v[24:27], v199, v232, v[24:27]
	v_and_or_b32 v47, v46, s29, v48
	ds_read_b32 v232, v47 offset:33024
	v_add_u32_e32 v46, v46, v45
	s_waitcnt vmcnt(13) lgkmcnt(15)
	v_mfma_f32_16x16x4_f32 v[24:27], v200, v233, v[24:27]
	v_and_or_b32 v47, v46, s29, v48
	ds_read_b32 v233, v47 offset:33024
	v_add_u32_e32 v46, v46, v45
	s_waitcnt vmcnt(12) lgkmcnt(15)
	v_mfma_f32_16x16x4_f32 v[24:27], v201, v234, v[24:27]
	v_and_or_b32 v47, v46, s29, v48
	ds_read_b32 v234, v47 offset:33024
	v_add_u32_e32 v46, v46, v45
	s_waitcnt vmcnt(11) lgkmcnt(15)
	v_mfma_f32_16x16x4_f32 v[24:27], v202, v235, v[24:27]
	v_and_or_b32 v47, v46, s29, v48
	ds_read_b32 v235, v47 offset:33024
	v_add_u32_e32 v46, v46, v45
	s_waitcnt vmcnt(10) lgkmcnt(15)
	v_mfma_f32_16x16x4_f32 v[24:27], v203, v236, v[24:27]
	v_and_or_b32 v47, v46, s29, v48
	ds_read_b32 v236, v47 offset:33024
	v_add_u32_e32 v46, v46, v45
	s_waitcnt vmcnt(9) lgkmcnt(15)
	v_mfma_f32_16x16x4_f32 v[24:27], v204, v237, v[24:27]
	v_and_or_b32 v47, v46, s29, v48
	ds_read_b32 v237, v47 offset:33024
	v_add_u32_e32 v46, v46, v45
	s_waitcnt vmcnt(8) lgkmcnt(15)
	v_mfma_f32_16x16x4_f32 v[24:27], v205, v238, v[24:27]
	v_and_or_b32 v47, v46, s29, v48
	ds_read_b32 v238, v47 offset:33024
	v_add_u32_e32 v46, v46, v45
	s_waitcnt vmcnt(7) lgkmcnt(15)
	v_mfma_f32_16x16x4_f32 v[24:27], v206, v239, v[24:27]
	v_and_or_b32 v47, v46, s29, v48
	ds_read_b32 v239, v47 offset:33024
	v_add_u32_e32 v46, v46, v45
	s_waitcnt vmcnt(6) lgkmcnt(15)
	v_mfma_f32_16x16x4_f32 v[24:27], v207, v240, v[24:27]
	v_and_or_b32 v47, v46, s29, v48
	ds_read_b32 v240, v47 offset:33024
	v_add_u32_e32 v46, v46, v45
	s_waitcnt vmcnt(5) lgkmcnt(15)
	v_mfma_f32_16x16x4_f32 v[24:27], v208, v241, v[24:27]
	v_and_or_b32 v47, v46, s29, v48
	ds_read_b32 v241, v47 offset:33024
	v_add_u32_e32 v46, v46, v45
	s_waitcnt vmcnt(4) lgkmcnt(15)
	v_mfma_f32_16x16x4_f32 v[24:27], v209, v242, v[24:27]
	v_and_or_b32 v47, v46, s29, v48
	ds_read_b32 v242, v47 offset:33024
	v_add_u32_e32 v46, v46, v45
	s_waitcnt vmcnt(3) lgkmcnt(15)
	v_mfma_f32_16x16x4_f32 v[24:27], v210, v243, v[24:27]
	v_and_or_b32 v47, v46, s29, v48
	ds_read_b32 v243, v47 offset:33024
	v_add_u32_e32 v46, v46, v45
	s_waitcnt vmcnt(2) lgkmcnt(15)
	v_mfma_f32_16x16x4_f32 v[24:27], v211, v244, v[24:27]
	v_and_or_b32 v47, v46, s29, v48
	ds_read_b32 v244, v47 offset:33024
	v_add_u32_e32 v46, v46, v45
	s_waitcnt vmcnt(1) lgkmcnt(15)
	v_mfma_f32_16x16x4_f32 v[24:27], v212, v245, v[24:27]
	v_and_or_b32 v47, v46, s29, v48
	ds_read_b32 v245, v47 offset:33024
	v_add_u32_e32 v46, v46, v45
	s_waitcnt vmcnt(0) lgkmcnt(15)
	v_mfma_f32_16x16x4_f32 v[24:27], v213, v246, v[24:27]
	v_and_or_b32 v47, v46, s29, v48
	ds_read_b32 v246, v47 offset:33024
	v_add_u32_e32 v46, v46, v45
	v_add_u32_e32 v44, 16, v42
	v_lshlrev_b32_e32 v45, 4, v44
	v_mul_u32_u24_e32 v46, v44, v12
	v_lshlrev_b32_e32 v46, 2, v46
	s_waitcnt lgkmcnt(15)
	v_mfma_f32_16x16x4_f32 v[28:31], v182, v214, v[28:31]
	v_and_or_b32 v47, v46, s29, v48
	ds_read_b32 v214, v47 offset:33024
	v_add_u32_e32 v46, v46, v45
	s_waitcnt lgkmcnt(15)
	v_mfma_f32_16x16x4_f32 v[28:31], v183, v215, v[28:31]
	v_and_or_b32 v47, v46, s29, v48
	ds_read_b32 v215, v47 offset:33024
	v_add_u32_e32 v46, v46, v45
	s_waitcnt lgkmcnt(15)
	v_mfma_f32_16x16x4_f32 v[28:31], v184, v216, v[28:31]
	v_and_or_b32 v47, v46, s29, v48
	ds_read_b32 v216, v47 offset:33024
	v_add_u32_e32 v46, v46, v45
	s_waitcnt lgkmcnt(15)
	v_mfma_f32_16x16x4_f32 v[28:31], v185, v217, v[28:31]
	v_and_or_b32 v47, v46, s29, v48
	ds_read_b32 v217, v47 offset:33024
	v_add_u32_e32 v46, v46, v45
	s_waitcnt lgkmcnt(15)
	v_mfma_f32_16x16x4_f32 v[28:31], v186, v218, v[28:31]
	v_and_or_b32 v47, v46, s29, v48
	ds_read_b32 v218, v47 offset:33024
	v_add_u32_e32 v46, v46, v45
	s_waitcnt lgkmcnt(15)
	v_mfma_f32_16x16x4_f32 v[28:31], v187, v219, v[28:31]
	v_and_or_b32 v47, v46, s29, v48
	ds_read_b32 v219, v47 offset:33024
	v_add_u32_e32 v46, v46, v45
	s_waitcnt lgkmcnt(15)
	v_mfma_f32_16x16x4_f32 v[28:31], v188, v221, v[28:31]
	v_and_or_b32 v47, v46, s29, v48
	ds_read_b32 v221, v47 offset:33024
	v_add_u32_e32 v46, v46, v45
	s_waitcnt lgkmcnt(15)
	v_mfma_f32_16x16x4_f32 v[28:31], v189, v222, v[28:31]
	v_and_or_b32 v47, v46, s29, v48
	ds_read_b32 v222, v47 offset:33024
	v_add_u32_e32 v46, v46, v45
	s_waitcnt lgkmcnt(15)
	v_mfma_f32_16x16x4_f32 v[28:31], v190, v223, v[28:31]
	v_and_or_b32 v47, v46, s29, v48
	ds_read_b32 v223, v47 offset:33024
	v_add_u32_e32 v46, v46, v45
	s_waitcnt lgkmcnt(15)
	v_mfma_f32_16x16x4_f32 v[28:31], v191, v224, v[28:31]
	v_and_or_b32 v47, v46, s29, v48
	ds_read_b32 v224, v47 offset:33024
	v_add_u32_e32 v46, v46, v45
	s_waitcnt lgkmcnt(15)
	v_mfma_f32_16x16x4_f32 v[28:31], v192, v225, v[28:31]
	v_and_or_b32 v47, v46, s29, v48
	ds_read_b32 v225, v47 offset:33024
	v_add_u32_e32 v46, v46, v45
	s_waitcnt lgkmcnt(15)
	v_mfma_f32_16x16x4_f32 v[28:31], v193, v226, v[28:31]
	v_and_or_b32 v47, v46, s29, v48
	ds_read_b32 v226, v47 offset:33024
	v_add_u32_e32 v46, v46, v45
	s_waitcnt lgkmcnt(15)
	v_mfma_f32_16x16x4_f32 v[28:31], v194, v227, v[28:31]
	v_and_or_b32 v47, v46, s29, v48
	ds_read_b32 v227, v47 offset:33024
	v_add_u32_e32 v46, v46, v45
	s_waitcnt lgkmcnt(15)
	v_mfma_f32_16x16x4_f32 v[28:31], v195, v228, v[28:31]
	v_and_or_b32 v47, v46, s29, v48
	ds_read_b32 v228, v47 offset:33024
	v_add_u32_e32 v46, v46, v45
	s_waitcnt lgkmcnt(15)
	v_mfma_f32_16x16x4_f32 v[28:31], v196, v229, v[28:31]
	v_and_or_b32 v47, v46, s29, v48
	ds_read_b32 v229, v47 offset:33024
	v_add_u32_e32 v46, v46, v45
	s_waitcnt lgkmcnt(15)
	v_mfma_f32_16x16x4_f32 v[28:31], v197, v230, v[28:31]
	v_and_or_b32 v47, v46, s29, v48
	ds_read_b32 v230, v47 offset:33024
	v_add_u32_e32 v46, v46, v45
	s_waitcnt lgkmcnt(15)
	v_mfma_f32_16x16x4_f32 v[28:31], v198, v231, v[28:31]
	v_and_or_b32 v47, v46, s29, v48
	ds_read_b32 v231, v47 offset:33024
	v_add_u32_e32 v46, v46, v45
	s_waitcnt lgkmcnt(15)
	v_mfma_f32_16x16x4_f32 v[28:31], v199, v232, v[28:31]
	v_and_or_b32 v47, v46, s29, v48
	ds_read_b32 v232, v47 offset:33024
	v_add_u32_e32 v46, v46, v45
	s_waitcnt lgkmcnt(15)
	v_mfma_f32_16x16x4_f32 v[28:31], v200, v233, v[28:31]
	v_and_or_b32 v47, v46, s29, v48
	ds_read_b32 v233, v47 offset:33024
	v_add_u32_e32 v46, v46, v45
	s_waitcnt lgkmcnt(15)
	v_mfma_f32_16x16x4_f32 v[28:31], v201, v234, v[28:31]
	v_and_or_b32 v47, v46, s29, v48
	ds_read_b32 v234, v47 offset:33024
	v_add_u32_e32 v46, v46, v45
	s_waitcnt lgkmcnt(15)
	v_mfma_f32_16x16x4_f32 v[28:31], v202, v235, v[28:31]
	v_and_or_b32 v47, v46, s29, v48
	ds_read_b32 v235, v47 offset:33024
	v_add_u32_e32 v46, v46, v45
	s_waitcnt lgkmcnt(15)
	v_mfma_f32_16x16x4_f32 v[28:31], v203, v236, v[28:31]
	v_and_or_b32 v47, v46, s29, v48
	ds_read_b32 v236, v47 offset:33024
	v_add_u32_e32 v46, v46, v45
	s_waitcnt lgkmcnt(15)
	v_mfma_f32_16x16x4_f32 v[28:31], v204, v237, v[28:31]
	v_and_or_b32 v47, v46, s29, v48
	ds_read_b32 v237, v47 offset:33024
	v_add_u32_e32 v46, v46, v45
	s_waitcnt lgkmcnt(15)
	v_mfma_f32_16x16x4_f32 v[28:31], v205, v238, v[28:31]
	v_and_or_b32 v47, v46, s29, v48
	ds_read_b32 v238, v47 offset:33024
	v_add_u32_e32 v46, v46, v45
	s_waitcnt lgkmcnt(15)
	v_mfma_f32_16x16x4_f32 v[28:31], v206, v239, v[28:31]
	v_and_or_b32 v47, v46, s29, v48
	ds_read_b32 v239, v47 offset:33024
	v_add_u32_e32 v46, v46, v45
	s_waitcnt lgkmcnt(15)
	v_mfma_f32_16x16x4_f32 v[28:31], v207, v240, v[28:31]
	v_and_or_b32 v47, v46, s29, v48
	ds_read_b32 v240, v47 offset:33024
	v_add_u32_e32 v46, v46, v45
	s_waitcnt lgkmcnt(15)
	v_mfma_f32_16x16x4_f32 v[28:31], v208, v241, v[28:31]
	v_and_or_b32 v47, v46, s29, v48
	ds_read_b32 v241, v47 offset:33024
	v_add_u32_e32 v46, v46, v45
	s_waitcnt lgkmcnt(15)
	v_mfma_f32_16x16x4_f32 v[28:31], v209, v242, v[28:31]
	v_and_or_b32 v47, v46, s29, v48
	ds_read_b32 v242, v47 offset:33024
	v_add_u32_e32 v46, v46, v45
	s_waitcnt lgkmcnt(15)
	v_mfma_f32_16x16x4_f32 v[28:31], v210, v243, v[28:31]
	v_and_or_b32 v47, v46, s29, v48
	ds_read_b32 v243, v47 offset:33024
	v_add_u32_e32 v46, v46, v45
	s_waitcnt lgkmcnt(15)
	v_mfma_f32_16x16x4_f32 v[28:31], v211, v244, v[28:31]
	v_and_or_b32 v47, v46, s29, v48
	ds_read_b32 v244, v47 offset:33024
	v_add_u32_e32 v46, v46, v45
	s_waitcnt lgkmcnt(15)
	v_mfma_f32_16x16x4_f32 v[28:31], v212, v245, v[28:31]
	v_and_or_b32 v47, v46, s29, v48
	ds_read_b32 v245, v47 offset:33024
	v_add_u32_e32 v46, v46, v45
	s_waitcnt lgkmcnt(15)
	v_mfma_f32_16x16x4_f32 v[28:31], v213, v246, v[28:31]
	v_and_or_b32 v47, v46, s29, v48
	ds_read_b32 v246, v47 offset:33024
	v_add_u32_e32 v46, v46, v45
	v_add_u32_e32 v44, 24, v42
	v_lshlrev_b32_e32 v45, 4, v44
	v_mul_u32_u24_e32 v46, v44, v12
	v_lshlrev_b32_e32 v46, 2, v46
	s_waitcnt lgkmcnt(15)
	v_mfma_f32_16x16x4_f32 v[32:35], v182, v214, v[32:35]
	v_and_or_b32 v47, v46, s29, v48
	ds_read_b32 v214, v47 offset:33024
	v_add_u32_e32 v46, v46, v45
	s_waitcnt lgkmcnt(15)
	v_mfma_f32_16x16x4_f32 v[32:35], v183, v215, v[32:35]
	v_and_or_b32 v47, v46, s29, v48
	ds_read_b32 v215, v47 offset:33024
	v_add_u32_e32 v46, v46, v45
	s_waitcnt lgkmcnt(15)
	v_mfma_f32_16x16x4_f32 v[32:35], v184, v216, v[32:35]
	v_and_or_b32 v47, v46, s29, v48
	ds_read_b32 v216, v47 offset:33024
	v_add_u32_e32 v46, v46, v45
	s_waitcnt lgkmcnt(15)
	v_mfma_f32_16x16x4_f32 v[32:35], v185, v217, v[32:35]
	v_and_or_b32 v47, v46, s29, v48
	ds_read_b32 v217, v47 offset:33024
	v_add_u32_e32 v46, v46, v45
	s_waitcnt lgkmcnt(15)
	v_mfma_f32_16x16x4_f32 v[32:35], v186, v218, v[32:35]
	v_and_or_b32 v47, v46, s29, v48
	ds_read_b32 v218, v47 offset:33024
	v_add_u32_e32 v46, v46, v45
	s_waitcnt lgkmcnt(15)
	v_mfma_f32_16x16x4_f32 v[32:35], v187, v219, v[32:35]
	v_and_or_b32 v47, v46, s29, v48
	ds_read_b32 v219, v47 offset:33024
	v_add_u32_e32 v46, v46, v45
	s_waitcnt lgkmcnt(15)
	v_mfma_f32_16x16x4_f32 v[32:35], v188, v221, v[32:35]
	v_and_or_b32 v47, v46, s29, v48
	ds_read_b32 v221, v47 offset:33024
	v_add_u32_e32 v46, v46, v45
	s_waitcnt lgkmcnt(15)
	v_mfma_f32_16x16x4_f32 v[32:35], v189, v222, v[32:35]
	v_and_or_b32 v47, v46, s29, v48
	ds_read_b32 v222, v47 offset:33024
	v_add_u32_e32 v46, v46, v45
	s_waitcnt lgkmcnt(15)
	v_mfma_f32_16x16x4_f32 v[32:35], v190, v223, v[32:35]
	v_and_or_b32 v47, v46, s29, v48
	ds_read_b32 v223, v47 offset:33024
	v_add_u32_e32 v46, v46, v45
	s_waitcnt lgkmcnt(15)
	v_mfma_f32_16x16x4_f32 v[32:35], v191, v224, v[32:35]
	v_and_or_b32 v47, v46, s29, v48
	ds_read_b32 v224, v47 offset:33024
	v_add_u32_e32 v46, v46, v45
	s_waitcnt lgkmcnt(15)
	v_mfma_f32_16x16x4_f32 v[32:35], v192, v225, v[32:35]
	v_and_or_b32 v47, v46, s29, v48
	ds_read_b32 v225, v47 offset:33024
	v_add_u32_e32 v46, v46, v45
	s_waitcnt lgkmcnt(15)
	v_mfma_f32_16x16x4_f32 v[32:35], v193, v226, v[32:35]
	v_and_or_b32 v47, v46, s29, v48
	ds_read_b32 v226, v47 offset:33024
	v_add_u32_e32 v46, v46, v45
	s_waitcnt lgkmcnt(15)
	v_mfma_f32_16x16x4_f32 v[32:35], v194, v227, v[32:35]
	v_and_or_b32 v47, v46, s29, v48
	ds_read_b32 v227, v47 offset:33024
	v_add_u32_e32 v46, v46, v45
	s_waitcnt lgkmcnt(15)
	v_mfma_f32_16x16x4_f32 v[32:35], v195, v228, v[32:35]
	v_and_or_b32 v47, v46, s29, v48
	ds_read_b32 v228, v47 offset:33024
	v_add_u32_e32 v46, v46, v45
	s_waitcnt lgkmcnt(15)
	v_mfma_f32_16x16x4_f32 v[32:35], v196, v229, v[32:35]
	v_and_or_b32 v47, v46, s29, v48
	ds_read_b32 v229, v47 offset:33024
	v_add_u32_e32 v46, v46, v45
	s_waitcnt lgkmcnt(15)
	v_mfma_f32_16x16x4_f32 v[32:35], v197, v230, v[32:35]
	v_and_or_b32 v47, v46, s29, v48
	ds_read_b32 v230, v47 offset:33024
	v_add_u32_e32 v46, v46, v45
	s_waitcnt lgkmcnt(15)
	v_mfma_f32_16x16x4_f32 v[32:35], v198, v231, v[32:35]
	v_and_or_b32 v47, v46, s29, v48
	ds_read_b32 v231, v47 offset:33024
	v_add_u32_e32 v46, v46, v45
	s_waitcnt lgkmcnt(15)
	v_mfma_f32_16x16x4_f32 v[32:35], v199, v232, v[32:35]
	v_and_or_b32 v47, v46, s29, v48
	ds_read_b32 v232, v47 offset:33024
	v_add_u32_e32 v46, v46, v45
	s_waitcnt lgkmcnt(15)
	v_mfma_f32_16x16x4_f32 v[32:35], v200, v233, v[32:35]
	v_and_or_b32 v47, v46, s29, v48
	ds_read_b32 v233, v47 offset:33024
	v_add_u32_e32 v46, v46, v45
	s_waitcnt lgkmcnt(15)
	v_mfma_f32_16x16x4_f32 v[32:35], v201, v234, v[32:35]
	v_and_or_b32 v47, v46, s29, v48
	ds_read_b32 v234, v47 offset:33024
	v_add_u32_e32 v46, v46, v45
	s_waitcnt lgkmcnt(15)
	v_mfma_f32_16x16x4_f32 v[32:35], v202, v235, v[32:35]
	v_and_or_b32 v47, v46, s29, v48
	ds_read_b32 v235, v47 offset:33024
	v_add_u32_e32 v46, v46, v45
	s_waitcnt lgkmcnt(15)
	v_mfma_f32_16x16x4_f32 v[32:35], v203, v236, v[32:35]
	v_and_or_b32 v47, v46, s29, v48
	ds_read_b32 v236, v47 offset:33024
	v_add_u32_e32 v46, v46, v45
	s_waitcnt lgkmcnt(15)
	v_mfma_f32_16x16x4_f32 v[32:35], v204, v237, v[32:35]
	v_and_or_b32 v47, v46, s29, v48
	ds_read_b32 v237, v47 offset:33024
	v_add_u32_e32 v46, v46, v45
	s_waitcnt lgkmcnt(15)
	v_mfma_f32_16x16x4_f32 v[32:35], v205, v238, v[32:35]
	v_and_or_b32 v47, v46, s29, v48
	ds_read_b32 v238, v47 offset:33024
	v_add_u32_e32 v46, v46, v45
	s_waitcnt lgkmcnt(15)
	v_mfma_f32_16x16x4_f32 v[32:35], v206, v239, v[32:35]
	v_and_or_b32 v47, v46, s29, v48
	ds_read_b32 v239, v47 offset:33024
	v_add_u32_e32 v46, v46, v45
	s_waitcnt lgkmcnt(15)
	v_mfma_f32_16x16x4_f32 v[32:35], v207, v240, v[32:35]
	v_and_or_b32 v47, v46, s29, v48
	ds_read_b32 v240, v47 offset:33024
	v_add_u32_e32 v46, v46, v45
	s_waitcnt lgkmcnt(15)
	v_mfma_f32_16x16x4_f32 v[32:35], v208, v241, v[32:35]
	v_and_or_b32 v47, v46, s29, v48
	ds_read_b32 v241, v47 offset:33024
	v_add_u32_e32 v46, v46, v45
	s_waitcnt lgkmcnt(15)
	v_mfma_f32_16x16x4_f32 v[32:35], v209, v242, v[32:35]
	v_and_or_b32 v47, v46, s29, v48
	ds_read_b32 v242, v47 offset:33024
	v_add_u32_e32 v46, v46, v45
	s_waitcnt lgkmcnt(15)
	v_mfma_f32_16x16x4_f32 v[32:35], v210, v243, v[32:35]
	v_and_or_b32 v47, v46, s29, v48
	ds_read_b32 v243, v47 offset:33024
	v_add_u32_e32 v46, v46, v45
	s_waitcnt lgkmcnt(15)
	v_mfma_f32_16x16x4_f32 v[32:35], v211, v244, v[32:35]
	v_and_or_b32 v47, v46, s29, v48
	ds_read_b32 v244, v47 offset:33024
	v_add_u32_e32 v46, v46, v45
	s_waitcnt lgkmcnt(15)
	v_mfma_f32_16x16x4_f32 v[32:35], v212, v245, v[32:35]
	v_and_or_b32 v47, v46, s29, v48
	ds_read_b32 v245, v47 offset:33024
	v_add_u32_e32 v46, v46, v45
	s_waitcnt lgkmcnt(15)
	v_mfma_f32_16x16x4_f32 v[32:35], v213, v246, v[32:35]
	v_and_or_b32 v47, v46, s29, v48
	ds_read_b32 v246, v47 offset:33024
	v_add_u32_e32 v46, v46, v45
	s_waitcnt lgkmcnt(15)
	v_mfma_f32_16x16x4_f32 v[36:39], v182, v214, v[36:39]
	s_waitcnt lgkmcnt(15)
	v_mfma_f32_16x16x4_f32 v[36:39], v183, v215, v[36:39]
	s_waitcnt lgkmcnt(15)
	v_mfma_f32_16x16x4_f32 v[36:39], v184, v216, v[36:39]
	s_waitcnt lgkmcnt(15)
	v_mfma_f32_16x16x4_f32 v[36:39], v185, v217, v[36:39]
	s_waitcnt lgkmcnt(15)
	v_mfma_f32_16x16x4_f32 v[36:39], v186, v218, v[36:39]
	s_waitcnt lgkmcnt(15)
	v_mfma_f32_16x16x4_f32 v[36:39], v187, v219, v[36:39]
	s_waitcnt lgkmcnt(15)
	v_mfma_f32_16x16x4_f32 v[36:39], v188, v221, v[36:39]
	s_waitcnt lgkmcnt(15)
	v_mfma_f32_16x16x4_f32 v[36:39], v189, v222, v[36:39]
	s_waitcnt lgkmcnt(15)
	v_mfma_f32_16x16x4_f32 v[36:39], v190, v223, v[36:39]
	s_waitcnt lgkmcnt(15)
	v_mfma_f32_16x16x4_f32 v[36:39], v191, v224, v[36:39]
	s_waitcnt lgkmcnt(15)
	v_mfma_f32_16x16x4_f32 v[36:39], v192, v225, v[36:39]
	s_waitcnt lgkmcnt(15)
	v_mfma_f32_16x16x4_f32 v[36:39], v193, v226, v[36:39]
	s_waitcnt lgkmcnt(15)
	v_mfma_f32_16x16x4_f32 v[36:39], v194, v227, v[36:39]
	s_waitcnt lgkmcnt(15)
	v_mfma_f32_16x16x4_f32 v[36:39], v195, v228, v[36:39]
	s_waitcnt lgkmcnt(15)
	v_mfma_f32_16x16x4_f32 v[36:39], v196, v229, v[36:39]
	s_waitcnt lgkmcnt(15)
	v_mfma_f32_16x16x4_f32 v[36:39], v197, v230, v[36:39]
	s_waitcnt lgkmcnt(15)
	v_mfma_f32_16x16x4_f32 v[36:39], v198, v231, v[36:39]
	s_waitcnt lgkmcnt(14)
	v_mfma_f32_16x16x4_f32 v[36:39], v199, v232, v[36:39]
	s_waitcnt lgkmcnt(13)
	v_mfma_f32_16x16x4_f32 v[36:39], v200, v233, v[36:39]
	s_waitcnt lgkmcnt(12)
	v_mfma_f32_16x16x4_f32 v[36:39], v201, v234, v[36:39]
	s_waitcnt lgkmcnt(11)
	v_mfma_f32_16x16x4_f32 v[36:39], v202, v235, v[36:39]
	s_waitcnt lgkmcnt(10)
	v_mfma_f32_16x16x4_f32 v[36:39], v203, v236, v[36:39]
	s_waitcnt lgkmcnt(9)
	v_mfma_f32_16x16x4_f32 v[36:39], v204, v237, v[36:39]
	s_waitcnt lgkmcnt(8)
	v_mfma_f32_16x16x4_f32 v[36:39], v205, v238, v[36:39]
	s_waitcnt lgkmcnt(7)
	v_mfma_f32_16x16x4_f32 v[36:39], v206, v239, v[36:39]
	s_waitcnt lgkmcnt(6)
	v_mfma_f32_16x16x4_f32 v[36:39], v207, v240, v[36:39]
	s_waitcnt lgkmcnt(5)
	v_mfma_f32_16x16x4_f32 v[36:39], v208, v241, v[36:39]
	s_waitcnt lgkmcnt(4)
	v_mfma_f32_16x16x4_f32 v[36:39], v209, v242, v[36:39]
	s_waitcnt lgkmcnt(3)
	v_mfma_f32_16x16x4_f32 v[36:39], v210, v243, v[36:39]
	s_waitcnt lgkmcnt(2)
	v_mfma_f32_16x16x4_f32 v[36:39], v211, v244, v[36:39]
	s_waitcnt lgkmcnt(1)
	v_mfma_f32_16x16x4_f32 v[36:39], v212, v245, v[36:39]
	s_waitcnt lgkmcnt(0)
	v_mfma_f32_16x16x4_f32 v[36:39], v213, v246, v[36:39]
	s_nop 7
	s_nop 3
	v_mul_f32_e32 v24, 0x3db504f3, v24
	v_mul_f32_e32 v25, 0x3db504f3, v25
	v_mul_f32_e32 v26, 0x3db504f3, v26
	v_mul_f32_e32 v27, 0x3db504f3, v27
	v_cvt_pk_bf16_f32 v24, v24, v25
	v_cvt_pk_bf16_f32 v25, v26, v27
	global_store_dwordx2 v40, v[24:25], s[34:35]
	v_add_u32_e32 v40, 0x10000, v40
	v_mul_f32_e32 v28, 0x3db504f3, v28
	v_mul_f32_e32 v29, 0x3db504f3, v29
	v_mul_f32_e32 v30, 0x3db504f3, v30
	v_mul_f32_e32 v31, 0x3db504f3, v31
	v_cvt_pk_bf16_f32 v28, v28, v29
	v_cvt_pk_bf16_f32 v29, v30, v31
	global_store_dwordx2 v40, v[28:29], s[34:35]
	v_add_u32_e32 v40, 0x10000, v40
	v_mul_f32_e32 v32, 0x3db504f3, v32
	v_mul_f32_e32 v33, 0x3db504f3, v33
	v_mul_f32_e32 v34, 0x3db504f3, v34
	v_mul_f32_e32 v35, 0x3db504f3, v35
	v_cvt_pk_bf16_f32 v32, v32, v33
	v_cvt_pk_bf16_f32 v33, v34, v35
	global_store_dwordx2 v40, v[32:33], s[34:35]
	v_add_u32_e32 v40, 0x10000, v40
	v_mul_f32_e32 v36, 0x3db504f3, v36
	v_mul_f32_e32 v37, 0x3db504f3, v37
	v_mul_f32_e32 v38, 0x3db504f3, v38
	v_mul_f32_e32 v39, 0x3db504f3, v39
	v_cvt_pk_bf16_f32 v36, v36, v37
	v_cvt_pk_bf16_f32 v37, v38, v39
	global_store_dwordx2 v40, v[36:37], s[34:35]
	s_branch .LBB0_21
